# phase 0->1 hand-off: the acquire invalidate is issued before the counter poll (overlapped with it) instead of after
# baseline (speedup 1.0000x reference)
.LBB0_71:
	s_cmp_gt_i32 s41, 1
	s_cselect_b64 s[0:1], -1, 0
	s_and_b64 s[4:5], s[0:1], s[4:5]
	s_andn2_b64 vcc, exec, s[4:5]
	s_cbranch_vccnz .LBB0_121
	s_cmpk_lg_i32 s56, 0x100
	s_cbranch_scc1 .Lq01_seam
	s_waitcnt vmcnt(0) lgkmcnt(0)
	s_cmp_lg_u32 s94, 0
	s_cbranch_scc1 .Lq01_wdone
	s_add_u32 s4, s54, 0xd603f80
	s_addc_u32 s5, s55, 0
	v_mov_b32_e32 v0, 0
	s_mov_b32 s9, 0
	buffer_inv sc1
.Lq01_poll:
	global_load_dword v1, v0, s[4:5] sc1
	s_waitcnt vmcnt(0)
	v_readfirstlane_b32 s10, v1
	s_cmpk_ge_u32 s10, 0xc0
	s_cbranch_scc1 .Lq01_pdone
	s_sleep 1
	s_add_i32 s9, s9, 1
	s_cmp_lt_u32 s9, 0x40000
	s_cbranch_scc1 .Lq01_poll
.Lq01_pdone:
	s_waitcnt vmcnt(0)
.Lq01_wdone:
	s_barrier
	s_branch .LBB0_121
